# attention: waves 4-7 hold the priority raise only over QK + softmax of each tile (dropped before the P.V part) instead of over the whole loop
# speedup vs baseline: 1.0023x; 1.0023x over previous
.LBB0_55:
	v_sub_u32_e64 v1, s40, v232 clamp
	s_min_u32 s30, s40, 0xe80
	s_addk_i32 s30, 0x180
	v_readfirstlane_b32 s31, v1
	s_lshr_b32 s35, s31, 6
	s_lshr_b32 s36, s30, 6
	s_and_b64 s[30:31], s[28:29], exec
	s_cselect_b32 s30, s41, s36
	s_cselect_b32 s40, 0, s35
	s_waitcnt vmcnt(0) lgkmcnt(0)
	s_barrier
	v_mov_b32_e32 v30, v0
	s_sub_i32 s41, s30, s40
	v_mov_b32_e32 v29, v0
	v_mov_b32_e32 v28, v0
	v_mov_b32_e32 v27, v0
	v_mov_b32_e32 v26, v0
	v_mov_b32_e32 v25, v0
	v_mov_b32_e32 v24, v0
	v_mov_b32_e32 v23, v0
	v_mov_b32_e32 v22, v0
	v_mov_b32_e32 v21, v0
	v_mov_b32_e32 v20, v0
	v_mov_b32_e32 v19, v0
	v_mov_b32_e32 v18, v0
	v_mov_b32_e32 v17, v0
	v_mov_b32_e32 v16, v0
	v_mov_b32_e32 v15, v0
	v_mov_b32_e32 v14, v0
	v_mov_b32_e32 v13, v0
	v_mov_b32_e32 v12, v0
	v_mov_b32_e32 v11, v0
	v_mov_b32_e32 v10, v0
	v_mov_b32_e32 v9, v0
	v_mov_b32_e32 v8, v0
	v_mov_b32_e32 v7, v0
	v_mov_b32_e32 v6, v0
	v_mov_b32_e32 v5, v0
	v_mov_b32_e32 v4, v0
	v_mov_b32_e32 v3, v0
	v_mov_b32_e32 v2, v0
	v_mov_b32_e32 v1, v0
	v_mov_b64_e32 v[62:63], v[30:31]
	s_cmp_gt_i32 s41, -4
	v_mov_b32_e32 v121, v113
	v_mov_b64_e32 v[32:33], v[0:1]
	v_mov_b64_e32 v[60:61], v[28:29]
	v_mov_b64_e32 v[58:59], v[26:27]
	v_mov_b64_e32 v[56:57], v[24:25]
	v_mov_b64_e32 v[54:55], v[22:23]
	v_mov_b64_e32 v[52:53], v[20:21]
	v_mov_b64_e32 v[50:51], v[18:19]
	v_mov_b64_e32 v[48:49], v[16:17]
	v_mov_b64_e32 v[46:47], v[14:15]
	v_mov_b64_e32 v[44:45], v[12:13]
	v_mov_b64_e32 v[42:43], v[10:11]
	v_mov_b64_e32 v[40:41], v[8:9]
	v_mov_b64_e32 v[38:39], v[6:7]
	v_mov_b64_e32 v[36:37], v[4:5]
	v_mov_b64_e32 v[34:35], v[2:3]
	s_cbranch_scc0 .LBB0_38
	s_lshl_b32 s42, s42, 12
	s_lshl_b32 s30, s43, 8
	s_add_i32 s41, s41, 4
	s_addk_i32 s42, 0xff00
	s_sub_i32 s30, 0, s30
	s_and_b64 s[28:29], s[28:29], exec
	s_cselect_b32 s28, 0xfffff000, s30
	s_lshl_b32 s29, s44, 7
	v_add_u32_e32 v123, s29, v112
	v_add_u32_e32 v125, s29, v114
	s_lshl_b32 s29, s40, 6
	s_add_i32 s29, s29, s28
	v_mov_b32_e32 v1, v0
	v_mov_b32_e32 v2, v0
	v_mov_b32_e32 v3, v0
	v_mov_b32_e32 v4, v0
	v_mov_b32_e32 v5, v0
	v_mov_b32_e32 v6, v0
	v_mov_b32_e32 v7, v0
	v_mov_b32_e32 v8, v0
	v_mov_b32_e32 v9, v0
	v_mov_b32_e32 v10, v0
	v_mov_b32_e32 v11, v0
	v_mov_b32_e32 v12, v0
	v_mov_b32_e32 v13, v0
	v_mov_b32_e32 v14, v0
	v_mov_b32_e32 v15, v0
	v_mov_b32_e32 v16, v0
	v_mov_b32_e32 v17, v0
	v_mov_b32_e32 v18, v0
	v_mov_b32_e32 v19, v0
	v_mov_b32_e32 v20, v0
	v_mov_b32_e32 v21, v0
	v_mov_b32_e32 v22, v0
	v_mov_b32_e32 v23, v0
	v_mov_b32_e32 v24, v0
	v_mov_b32_e32 v25, v0
	v_mov_b32_e32 v26, v0
	v_mov_b32_e32 v27, v0
	v_mov_b32_e32 v28, v0
	v_mov_b32_e32 v29, v0
	v_mov_b32_e32 v30, v0
	v_mov_b32_e32 v31, v0
	s_waitcnt vmcnt(0)
	v_mul_f32_e32 v131, 0x3fb8aa3b, v64
	v_sub_f32_e32 v154, 0, v131
	v_mov_b32_e32 v155, v154
	v_mov_b32_e32 v156, v154
	v_mov_b32_e32 v157, v154
	v_mov_b32_e32 v158, v154
	v_mov_b32_e32 v159, v154
	v_mov_b32_e32 v160, v154
	v_mov_b32_e32 v161, v154
	v_mov_b32_e32 v162, v154
	v_mov_b32_e32 v163, v154
	v_mov_b32_e32 v164, v154
	v_mov_b32_e32 v165, v154
	v_mov_b32_e32 v166, v154
	v_mov_b32_e32 v167, v154
	v_mov_b32_e32 v168, v154
	v_mov_b32_e32 v169, v154
	s_mov_b32 s43, 0
	v_add_u32_e32 v127, s29, v134
	s_add_i32 s44, s34, 0x80
	s_mov_b32 s45, 2
	s_mov_b32 s46, 1
	v_mov_b32_e32 v121, v113
	s_mov_b32 s48, 0
	s_mov_b32 s47, 0
	s_mul_i32 s34, s48, 0x2400
	v_add_u32_e32 v208, s34, v115
	s_mul_i32 s34, s48, 0x2400
	v_add_u32_e32 v209, s34, v133
	v_readfirstlane_b32 s99, v191
	s_lshr_b32 s99, s99, 8

.Latt_swa_nomasktest:
	s_cmp_lg_u32 s99, 0
	s_cbranch_scc0 .Latt_swa_pt
	s_setprio 1

.Latt_swa_norescale:
	s_cmp_lg_u32 s99, 0
	s_cbranch_scc0 .Latt_swa_pm
	s_setprio 0

.LBB0_106:
	v_mov_b32_e32 v14, v0
	v_mov_b32_e32 v15, v0
	s_waitcnt vmcnt(0) lgkmcnt(0)
	s_barrier
	v_mov_b32_e32 v1, v0
	v_mov_b32_e32 v2, v0
	v_mov_b32_e32 v3, v0
	v_mov_b32_e32 v4, v0
	v_mov_b32_e32 v5, v0
	v_mov_b32_e32 v6, v0
	v_mov_b32_e32 v7, v0
	v_mov_b32_e32 v8, v0
	v_mov_b32_e32 v9, v0
	v_mov_b32_e32 v10, v0
	v_mov_b32_e32 v11, v0
	v_mov_b32_e32 v12, v0
	v_mov_b32_e32 v13, v0
	s_lshl_b32 s30, s43, 12
	s_lshl_b32 s44, s48, 7
	v_mov_b64_e32 v[62:63], v[14:15]
	v_mov_b64_e32 v[46:47], v[14:15]
	v_mov_b64_e32 v[30:31], v[14:15]
	s_add_i32 s43, s30, 0xffffff80
	v_add_u32_e32 v153, s44, v171
	v_add_u32_e32 v155, s44, v172
	s_add_i32 s45, s46, 0x80
	s_mov_b32 s50, 2
	s_mov_b32 s51, 1
	s_mov_b32 s53, 0
	v_mov_b32_e32 v157, 0
	v_mov_b32_e32 v159, 0
	v_mov_b32_e32 v96, 0
	v_mov_b32_e32 v97, 0
	v_mov_b32_e32 v98, 0
	v_mov_b32_e32 v99, 0
	v_mov_b32_e32 v100, 0
	v_mov_b32_e32 v101, 0
	v_mov_b32_e32 v102, 0
	v_mov_b32_e32 v103, 0
	v_mov_b32_e32 v104, 0
	v_mov_b32_e32 v105, 0
	v_mov_b32_e32 v106, 0
	v_mov_b32_e32 v107, 0
	v_mov_b32_e32 v108, 0
	v_mov_b32_e32 v109, 0
	v_mov_b32_e32 v110, 0
	v_mov_b32_e32 v111, 0
	v_mov_b64_e32 v[60:61], v[12:13]
	v_mov_b64_e32 v[58:59], v[10:11]
	v_mov_b64_e32 v[56:57], v[8:9]
	v_mov_b64_e32 v[54:55], v[6:7]
	v_mov_b64_e32 v[52:53], v[4:5]
	v_mov_b64_e32 v[50:51], v[2:3]
	v_mov_b64_e32 v[48:49], v[0:1]
	v_mov_b64_e32 v[44:45], v[12:13]
	v_mov_b64_e32 v[42:43], v[10:11]
	v_mov_b64_e32 v[40:41], v[8:9]
	v_mov_b64_e32 v[38:39], v[6:7]
	v_mov_b64_e32 v[36:37], v[4:5]
	v_mov_b64_e32 v[34:35], v[2:3]
	v_mov_b64_e32 v[32:33], v[0:1]
	v_mov_b64_e32 v[28:29], v[12:13]
	v_mov_b64_e32 v[26:27], v[10:11]
	v_mov_b64_e32 v[24:25], v[8:9]
	v_mov_b64_e32 v[22:23], v[6:7]
	v_mov_b64_e32 v[20:21], v[4:5]
	v_mov_b64_e32 v[18:19], v[2:3]
	v_mov_b64_e32 v[16:17], v[0:1]
	s_mov_b32 s52, 0
	s_waitcnt vmcnt(0)
	s_mul_i32 s30, s53, 0x2400
	v_add_u32_e32 v242, s30, v173
	s_mul_i32 s30, s53, 0x4800
	v_add_u32_e32 v243, s30, v174
	v_readfirstlane_b32 s99, v191
	s_lshr_b32 s99, s99, 8
.LBB0_107:
.LBB0_116:
	s_cmp_lg_u32 s99, 0
	s_cbranch_scc0 .Latt_diff_pt
	s_setprio 1

.LBB0_177:
	v_mov_b32_e32 v14, v0
	v_mov_b32_e32 v15, v0
	s_waitcnt vmcnt(0) lgkmcnt(0)
	s_barrier
	v_mov_b32_e32 v1, v0
	v_mov_b32_e32 v2, v0
	v_mov_b32_e32 v3, v0
	v_mov_b32_e32 v4, v0
	v_mov_b32_e32 v5, v0
	v_mov_b32_e32 v6, v0
	v_mov_b32_e32 v7, v0
	v_mov_b32_e32 v8, v0
	v_mov_b32_e32 v9, v0
	v_mov_b32_e32 v10, v0
	v_mov_b32_e32 v11, v0
	v_mov_b32_e32 v12, v0
	v_mov_b32_e32 v13, v0
	s_lshl_b32 s49, s49, 12
	v_mov_b64_e32 v[30:31], v[14:15]
	v_mov_b64_e32 v[46:47], v[14:15]
	v_mov_b64_e32 v[62:63], v[14:15]
	v_mad_u64_u32 v[222:223], s[30:31], s50, v238, v[190:191]
	v_mad_u64_u32 v[224:225], s[30:31], s50, v240, v[192:193]
	v_mad_u64_u32 v[226:227], s[30:31], s50, v242, v[194:195]
	v_mad_u64_u32 v[228:229], s[30:31], s50, v244, v[196:197]
	s_addk_i32 s49, 0xff80
	s_add_i32 s51, s60, 0x80
	s_mov_b32 s52, 2
	s_mov_b32 s53, 1
	s_mov_b32 s56, 0
	v_mov_b32_e32 v205, 0
	v_mov_b32_e32 v207, 0
	v_mov_b32_e32 v96, 0
	v_mov_b32_e32 v97, 0
	v_mov_b32_e32 v98, 0
	v_mov_b32_e32 v99, 0
	v_mov_b32_e32 v100, 0
	v_mov_b32_e32 v101, 0
	v_mov_b32_e32 v102, 0
	v_mov_b32_e32 v103, 0
	v_mov_b32_e32 v104, 0
	v_mov_b32_e32 v105, 0
	v_mov_b32_e32 v106, 0
	v_mov_b32_e32 v107, 0
	v_mov_b32_e32 v108, 0
	v_mov_b32_e32 v109, 0
	v_mov_b32_e32 v110, 0
	v_mov_b32_e32 v111, 0
	v_mov_b64_e32 v[28:29], v[12:13]
	v_mov_b64_e32 v[26:27], v[10:11]
	v_mov_b64_e32 v[24:25], v[8:9]
	v_mov_b64_e32 v[22:23], v[6:7]
	v_mov_b64_e32 v[20:21], v[4:5]
	v_mov_b64_e32 v[18:19], v[2:3]
	v_mov_b64_e32 v[16:17], v[0:1]
	v_mov_b64_e32 v[44:45], v[12:13]
	v_mov_b64_e32 v[42:43], v[10:11]
	v_mov_b64_e32 v[40:41], v[8:9]
	v_mov_b64_e32 v[38:39], v[6:7]
	v_mov_b64_e32 v[36:37], v[4:5]
	v_mov_b64_e32 v[34:35], v[2:3]
	v_mov_b64_e32 v[32:33], v[0:1]
	v_mov_b64_e32 v[60:61], v[12:13]
	v_mov_b64_e32 v[58:59], v[10:11]
	v_mov_b64_e32 v[56:57], v[8:9]
	v_mov_b64_e32 v[54:55], v[6:7]
	v_mov_b64_e32 v[52:53], v[4:5]
	v_mov_b64_e32 v[50:51], v[2:3]
	v_mov_b64_e32 v[48:49], v[0:1]
	s_mov_b32 s55, 0
	s_waitcnt vmcnt(0)
	s_mul_i32 s30, s56, 0x6400
	v_add_u32_e32 v209, s30, v246
	s_mul_i32 s30, s56, 0x4800
	v_add_u32_e32 v219, s30, v247
	v_readfirstlane_b32 s99, v191
	s_lshr_b32 s99, s99, 8
